# attention: s_setprio 1 over the stick-breaking VALU sections, 0 over the MFMA chains (inverse priority) on top of v_n9
# baseline (speedup 1.0000x reference)
; __device__ __forceinline__ int crow(int r, int hi) { return (r & 3) + 8 * (r >> 2) + 4 * hi; }
; __device__ __forceinline__ void sb_half(f32x16& pz, float& run, bool need_mask, int kb, int t, int hi) {
;     ...
;   for (int r = 0; r < 16; ++r) {
;     const float e = __builtin_amdgcn_exp2f(fminf(pz[r] * C2, 60.f));
;     l[r] = __builtin_amdgcn_rcpf(1.f + e);
;     pz[r] = e;
;   }
;   if (need_mask) {
; #pragma unroll
;     for (int r = 0; r < 16; ++r) { if (kb + crow(r, hi) >= t) { l[r] = 1.f; pz[r] = 0.f; } }
;   }
; __device__ __forceinline__ void attn_phase(const Params& p, char* smem, int bid, int nblk) {
;     ...
;         if (k0 + 32 <= tmax) {
;           f32x16 pz;
; #pragma unroll
;           for (int r = 0; r < 16; ++r) pz[r] = 0.f;
; #pragma unroll
;           for (int d0 = 0; d0 < 8; ++d0) {
;             const bf16x8 kf = *(const bf16x8*)(K_lds + KSWZ(32 + r32, (d0 * 16 + hi * 8) * 2));
;             pz = __builtin_amdgcn_mfma_f32_32x32x16_bf16(kf, qr[d0], pz, 0, 0, 0);
;           }
;           sb_half(pz, run, k0 + 63 >= tmin, k0 + 32, t, hi);
.LBB0_1790:
	s_sub_i32 s0, s55, 63
	s_lshl_b32 s56, s53, 15
	v_cmp_le_i32_e32 vcc, s0, v173
	s_and_saveexec_b64 s[44:45], vcc
	s_cbranch_execz .LBB0_1802
	s_sub_i32 s0, s55, 31
	v_add_u32_e32 v64, s56, v194
	v_cmp_le_i32_e32 vcc, s0, v173
	v_add_u32_e32 v186, v64, v205
	v_add_u32_e32 v185, v64, v206
	v_add_u32_e32 v184, v64, v207
	v_add_u32_e32 v183, v64, v208
	v_add_u32_e32 v182, v64, v209
	v_add_u32_e32 v181, v64, v210
	v_add_u32_e32 v180, v64, v211
	v_add_u32_e32 v175, v64, v212
	s_and_saveexec_b64 s[48:49], vcc
	s_cbranch_execz .Lattn_zero
	ds_read_b128 v[64:67], v186 offset:8192
	ds_read_b128 v[144:147], v185 offset:8192
	v_cmp_ge_i32_e32 vcc, s55, v230
	s_waitcnt lgkmcnt(1)
	v_mfma_f32_32x32x16_bf16 v[64:79], v[64:67], v[80:83], 0
	s_waitcnt lgkmcnt(0)
	v_mfma_f32_32x32x16_bf16 v[64:79], v[144:147], v[84:87], v[64:79]
	ds_read_b128 v[144:147], v184 offset:8192
	ds_read_b128 v[148:151], v183 offset:8192
	s_waitcnt lgkmcnt(1)
	v_mfma_f32_32x32x16_bf16 v[64:79], v[144:147], v[88:91], v[64:79]
	s_waitcnt lgkmcnt(0)
	v_mfma_f32_32x32x16_bf16 v[64:79], v[148:151], v[92:95], v[64:79]
	ds_read_b128 v[144:147], v182 offset:8192
	ds_read_b128 v[148:151], v181 offset:8192
	s_waitcnt lgkmcnt(1)
	v_mfma_f32_32x32x16_bf16 v[64:79], v[144:147], v[96:99], v[64:79]
	s_waitcnt lgkmcnt(0)
	v_mfma_f32_32x32x16_bf16 v[64:79], v[148:151], v[100:103], v[64:79]
	ds_read_b128 v[144:147], v180 offset:8192
	ds_read_b128 v[148:151], v175 offset:8192
	s_waitcnt lgkmcnt(1)
	v_mfma_f32_32x32x16_bf16 v[64:79], v[144:147], v[104:107], v[64:79]
	s_waitcnt lgkmcnt(0)
	v_mfma_f32_32x32x16_bf16 v[64:79], v[148:151], v[108:111], v[64:79]
	s_setprio 1
	s_nop 11
	v_mul_f32_e32 v64, 0x3e0293ee, v64
	v_mul_f32_e32 v67, 0x3e0293ee, v67
	v_mul_f32_e32 v68, 0x3e0293ee, v68
	v_mul_f32_e32 v71, 0x3e0293ee, v71
	v_min_f32_e32 v64, 0x42700000, v64
	v_min_f32_e32 v67, 0x42700000, v67
	v_min_f32_e32 v68, 0x42700000, v68
	v_min_f32_e32 v144, 0x42700000, v71
	v_exp_f32_e32 v71, v64
	v_exp_f32_e32 v187, v67
	v_exp_f32_e32 v234, v68
	v_mul_f32_e32 v66, 0x3e0293ee, v66
	v_mul_f32_e32 v72, 0x3e0293ee, v72
	v_mul_f32_e32 v74, 0x3e0293ee, v74
	v_mul_f32_e32 v75, 0x3e0293ee, v75
	v_mul_f32_e32 v76, 0x3e0293ee, v76
	v_min_f32_e32 v66, 0x42700000, v66
	v_min_f32_e32 v72, 0x42700000, v72
	v_mul_f32_e32 v70, 0x3e0293ee, v70
	v_mul_f32_e32 v73, 0x3e0293ee, v73
	v_mul_f32_e32 v77, 0x3e0293ee, v77
	v_min_f32_e32 v74, 0x42700000, v74
	v_min_f32_e32 v75, 0x42700000, v75
	v_min_f32_e32 v76, 0x42700000, v76
	v_exp_f32_e32 v178, v66
	v_exp_f32_e32 v235, v72
	v_add_f32_e32 v66, 1.0, v71
	v_add_f32_e32 v72, 1.0, v187
	v_mul_f32_e32 v65, 0x3e0293ee, v65
	v_min_f32_e32 v70, 0x42700000, v70
	v_min_f32_e32 v145, 0x42700000, v73
	v_min_f32_e32 v77, 0x42700000, v77
	v_exp_f32_e32 v231, v144
	v_exp_f32_e32 v64, v74
	v_exp_f32_e32 v232, v75
	v_exp_f32_e32 v237, v76
	v_add_f32_e32 v75, 1.0, v234
	v_rcp_f32_e32 v74, v66
	v_rcp_f32_e32 v66, v72
	v_mul_f32_e32 v72, 0x3e0293ee, v78
	v_mul_f32_e32 v69, 0x3e0293ee, v69
	v_min_f32_e32 v65, 0x42700000, v65
	v_exp_f32_e32 v70, v70
	v_exp_f32_e32 v67, v145
	v_exp_f32_e32 v236, v77
	v_rcp_f32_e32 v77, v75
	v_min_f32_e32 v72, 0x42700000, v72
	v_mul_f32_e32 v75, 0x3e0293ee, v79
	v_min_f32_e32 v69, 0x42700000, v69
	v_exp_f32_e32 v65, v65
	v_exp_f32_e32 v72, v72
	v_min_f32_e32 v75, 0x42700000, v75
	v_exp_f32_e32 v73, v69
	v_add_f32_e32 v69, 1.0, v178
	v_exp_f32_e32 v78, v75
	v_add_f32_e32 v147, 1.0, v231
	v_rcp_f32_e32 v144, v69
	v_add_f32_e32 v69, 1.0, v237
	v_add_f32_e32 v146, 1.0, v70
	v_add_f32_e32 v148, 1.0, v235
	v_add_f32_e32 v149, 1.0, v67
	v_rcp_f32_e32 v233, v147
	v_rcp_f32_e32 v147, v69
	v_add_f32_e32 v69, 1.0, v236
	v_add_f32_e32 v68, 1.0, v65
	v_add_f32_e32 v151, 1.0, v232
	v_rcp_f32_e32 v238, v146
	v_rcp_f32_e32 v146, v148
	v_rcp_f32_e32 v148, v149
	v_rcp_f32_e32 v149, v69
	v_add_f32_e32 v69, 1.0, v72
	v_add_f32_e32 v145, 1.0, v73
	v_add_f32_e32 v150, 1.0, v64
	v_rcp_f32_e32 v76, v68
	v_rcp_f32_e32 v68, v151
	v_rcp_f32_e32 v151, v69
	v_add_f32_e32 v69, 1.0, v78
	v_rcp_f32_e32 v145, v145
	v_rcp_f32_e32 v150, v150
	v_rcp_f32_e32 v69, v69
	s_and_saveexec_b64 s[50:51], vcc
	s_cbranch_execz .LBB0_1796
; __device__ __forceinline__ int crow(int r, int hi) { return (r & 3) + 8 * (r >> 2) + 4 * hi; }
; __device__ __forceinline__ void sb_half(f32x16& pz, float& run, bool need_mask, int kb, int t, int hi) {
;     ...
;   if (need_mask) {
; #pragma unroll
;     for (int r = 0; r < 16; ++r) { if (kb + crow(r, hi) >= t) { l[r] = 1.f; pz[r] = 0.f; } }
;   }
	v_add_u32_e32 v75, s55, v195
	v_subrev_u32_e32 v79, 31, v75
	v_cmp_lt_i32_e32 vcc, v79, v174
	v_subrev_u32_e32 v79, 30, v75
	v_cmp_lt_i32_e64 s[0:1], v79, v174
	v_subrev_u32_e32 v79, 29, v75
	v_cmp_lt_i32_e64 s[6:7], v79, v174
	v_subrev_u32_e32 v79, 28, v75
	v_cmp_lt_i32_e64 s[8:9], v79, v174
	v_subrev_u32_e32 v79, 23, v75
	v_cmp_lt_i32_e64 s[10:11], v79, v174
	v_subrev_u32_e32 v79, 22, v75
	v_cmp_lt_i32_e64 s[12:13], v79, v174
	v_subrev_u32_e32 v79, 21, v75
	v_cmp_lt_i32_e64 s[14:15], v79, v174
	v_subrev_u32_e32 v79, 20, v75
	v_cmp_lt_i32_e64 s[16:17], v79, v174
	v_add_u32_e32 v79, -15, v75
	v_cmp_lt_i32_e64 s[18:19], v79, v174
	v_add_u32_e32 v79, -14, v75
	v_cmp_lt_i32_e64 s[20:21], v79, v174
	v_add_u32_e32 v79, -13, v75
	v_cmp_lt_i32_e64 s[22:23], v79, v174
	v_add_u32_e32 v79, -12, v75
	v_cmp_lt_i32_e64 s[24:25], v79, v174
	v_add_u32_e32 v79, -7, v75
	v_cmp_lt_i32_e64 s[26:27], v79, v174
	v_add_u32_e32 v79, -6, v75
	v_cmp_lt_i32_e64 s[28:29], v79, v174
	v_add_u32_e32 v79, -5, v75
	v_cmp_lt_i32_e64 s[30:31], v79, v174
	s_or_b64 s[28:29], s[30:31], s[28:29]
	s_or_b64 s[26:27], s[28:29], s[26:27]
	s_or_b64 s[24:25], s[26:27], s[24:25]
	s_or_b64 s[22:23], s[24:25], s[22:23]
	s_or_b64 s[20:21], s[22:23], s[20:21]
	s_or_b64 s[18:19], s[20:21], s[18:19]
	s_or_b64 s[16:17], s[18:19], s[16:17]
	s_or_b64 s[14:15], s[16:17], s[14:15]
	s_or_b64 s[12:13], s[14:15], s[12:13]
	s_or_b64 s[10:11], s[12:13], s[10:11]
	s_or_b64 s[8:9], s[10:11], s[8:9]
	s_or_b64 s[6:7], s[8:9], s[6:7]
	s_or_b64 s[0:1], s[6:7], s[0:1]
	s_or_b64 vcc, s[0:1], vcc
	v_add_u32_e32 v75, -4, v75
	v_cndmask_b32_e64 v72, 0, v72, s[30:31]
	v_cndmask_b32_e64 v236, 0, v236, s[28:29]
	v_cndmask_b32_e64 v237, 0, v237, s[26:27]
	v_cndmask_b32_e64 v232, 0, v232, s[24:25]
	v_cndmask_b32_e64 v64, 0, v64, s[22:23]
	v_cndmask_b32_e64 v67, 0, v67, s[20:21]
	v_cndmask_b32_e64 v235, 0, v235, s[18:19]
	v_cndmask_b32_e64 v231, 0, v231, s[16:17]
	v_cndmask_b32_e64 v70, 0, v70, s[14:15]
	v_cndmask_b32_e64 v73, 0, v73, s[12:13]
	v_cndmask_b32_e64 v234, 0, v234, s[10:11]
	v_cndmask_b32_e64 v187, 0, v187, s[8:9]
	v_cndmask_b32_e64 v178, 0, v178, s[6:7]
	v_cndmask_b32_e64 v65, 0, v65, s[0:1]
	v_cndmask_b32_e32 v71, 0, v71, vcc
	v_cndmask_b32_e64 v149, 1.0, v149, s[28:29]
	v_cndmask_b32_e64 v147, 1.0, v147, s[26:27]
	v_cndmask_b32_e64 v68, 1.0, v68, s[24:25]
	v_cndmask_b32_e64 v150, 1.0, v150, s[22:23]
	v_cndmask_b32_e64 v148, 1.0, v148, s[20:21]
	v_cndmask_b32_e64 v146, 1.0, v146, s[18:19]
	v_cndmask_b32_e64 v233, 1.0, v233, s[16:17]
	v_cndmask_b32_e64 v238, 1.0, v238, s[14:15]
	v_cndmask_b32_e64 v145, 1.0, v145, s[12:13]
	v_cndmask_b32_e64 v77, 1.0, v77, s[10:11]
	v_cndmask_b32_e64 v66, 1.0, v66, s[8:9]
	v_cndmask_b32_e64 v144, 1.0, v144, s[6:7]
	v_cndmask_b32_e64 v76, 1.0, v76, s[0:1]
	v_cndmask_b32_e32 v74, 1.0, v74, vcc
	v_cndmask_b32_e64 v151, 1.0, v151, s[30:31]
	v_cmp_ge_i32_e32 vcc, v75, v174
	s_and_saveexec_b64 s[0:1], vcc
	v_mov_b32_e32 v78, 0
	v_mov_b32_e32 v69, 1.0
	s_or_b64 exec, exec, s[0:1]

; __device__ __forceinline__ int crow(int r, int hi) { return (r & 3) + 8 * (r >> 2) + 4 * hi; }
; __device__ __forceinline__ void sb_half(f32x16& pz, float& run, bool need_mask, int kb, int t, int hi) {
;     ...
;   for (int r = 0; r < 16; ++r) {
;     const float e = __builtin_amdgcn_exp2f(fminf(pz[r] * C2, 60.f));
;     l[r] = __builtin_amdgcn_rcpf(1.f + e);
;     pz[r] = e;
;   }
;   if (need_mask) {
; #pragma unroll
;     for (int r = 0; r < 16; ++r) { if (kb + crow(r, hi) >= t) { l[r] = 1.f; pz[r] = 0.f; } }
;   }
; __device__ __forceinline__ void attn_phase(const Params& p, char* smem, int bid, int nblk) {
;     ...
;         {
;           f32x16 pz;
; #pragma unroll
;           for (int r = 0; r < 16; ++r) pz[r] = 0.f;
; #pragma unroll
;           for (int d0 = 0; d0 < 8; ++d0) {
;             const bf16x8 kf = *(const bf16x8*)(K_lds + KSWZ(r32, (d0 * 16 + hi * 8) * 2));
;             pz = __builtin_amdgcn_mfma_f32_32x32x16_bf16(kf, qr[d0], pz, 0, 0, 0);
;           }
;           sb_half(pz, run, k0 + 31 >= tmin, k0, t, hi);
.LBB0_1797:
	s_or_b64 exec, exec, s[48:49]
	ds_read_b128 v[64:67], v186
	ds_read_b128 v[232:235], v185
	s_sub_i32 s0, s55, 32
	v_cmp_ge_i32_e32 vcc, s0, v230
	s_waitcnt lgkmcnt(1)
	s_setprio 0
	v_mfma_f32_32x32x16_bf16 v[64:79], v[64:67], v[80:83], 0
	s_waitcnt lgkmcnt(0)
	v_mfma_f32_32x32x16_bf16 v[64:79], v[232:235], v[84:87], v[64:79]
	ds_read_b128 v[184:187], v184
	ds_read_b128 v[232:235], v183
	s_waitcnt lgkmcnt(1)
	v_mfma_f32_32x32x16_bf16 v[64:79], v[184:187], v[88:91], v[64:79]
	s_waitcnt lgkmcnt(0)
	v_mfma_f32_32x32x16_bf16 v[64:79], v[232:235], v[92:95], v[64:79]
	ds_read_b128 v[182:185], v182
	ds_read_b128 v[232:235], v181
	s_waitcnt lgkmcnt(1)
	v_mfma_f32_32x32x16_bf16 v[64:79], v[182:185], v[96:99], v[64:79]
	ds_read_b128 v[180:183], v180
	ds_read_b128 v[184:187], v175
	s_waitcnt lgkmcnt(2)
	v_mfma_f32_32x32x16_bf16 v[64:79], v[232:235], v[100:103], v[64:79]
	s_waitcnt lgkmcnt(1)
	v_mfma_f32_32x32x16_bf16 v[64:79], v[180:183], v[104:107], v[64:79]
	s_waitcnt lgkmcnt(0)
	v_mfma_f32_32x32x16_bf16 v[64:79], v[184:187], v[108:111], v[64:79]
	s_setprio 1
	s_nop 11
	v_mul_f32_e32 v64, 0x3e0293ee, v64
	v_mul_f32_e32 v67, 0x3e0293ee, v67
	v_mul_f32_e32 v68, 0x3e0293ee, v68
	v_mul_f32_e32 v71, 0x3e0293ee, v71
	v_min_f32_e32 v64, 0x42700000, v64
	v_min_f32_e32 v67, 0x42700000, v67
	v_min_f32_e32 v68, 0x42700000, v68
	v_min_f32_e32 v180, 0x42700000, v71
	v_exp_f32_e32 v71, v64
	v_exp_f32_e32 v175, v67
	v_exp_f32_e32 v234, v68
	v_mul_f32_e32 v66, 0x3e0293ee, v66
	v_mul_f32_e32 v72, 0x3e0293ee, v72
	v_mul_f32_e32 v74, 0x3e0293ee, v74
	v_mul_f32_e32 v75, 0x3e0293ee, v75
	v_mul_f32_e32 v76, 0x3e0293ee, v76
	v_min_f32_e32 v66, 0x42700000, v66
	v_min_f32_e32 v72, 0x42700000, v72
	v_mul_f32_e32 v70, 0x3e0293ee, v70
	v_mul_f32_e32 v73, 0x3e0293ee, v73
	v_mul_f32_e32 v77, 0x3e0293ee, v77
	v_min_f32_e32 v74, 0x42700000, v74
	v_min_f32_e32 v75, 0x42700000, v75
	v_min_f32_e32 v76, 0x42700000, v76
	v_exp_f32_e32 v178, v66
	v_exp_f32_e32 v235, v72
	v_add_f32_e32 v66, 1.0, v71
	v_add_f32_e32 v72, 1.0, v175
	v_mul_f32_e32 v65, 0x3e0293ee, v65
	v_min_f32_e32 v70, 0x42700000, v70
	v_min_f32_e32 v181, 0x42700000, v73
	v_min_f32_e32 v77, 0x42700000, v77
	v_exp_f32_e32 v231, v180
	v_exp_f32_e32 v64, v74
	v_exp_f32_e32 v232, v75
	v_exp_f32_e32 v237, v76
	v_add_f32_e32 v75, 1.0, v234
	v_rcp_f32_e32 v74, v66
	v_rcp_f32_e32 v66, v72
	v_mul_f32_e32 v72, 0x3e0293ee, v78
	v_mul_f32_e32 v69, 0x3e0293ee, v69
	v_min_f32_e32 v65, 0x42700000, v65
	v_exp_f32_e32 v70, v70
	v_exp_f32_e32 v67, v181
	v_exp_f32_e32 v236, v77
	v_rcp_f32_e32 v77, v75
	v_min_f32_e32 v72, 0x42700000, v72
	v_mul_f32_e32 v75, 0x3e0293ee, v79
	v_min_f32_e32 v69, 0x42700000, v69
	v_exp_f32_e32 v65, v65
	v_exp_f32_e32 v72, v72
	v_min_f32_e32 v75, 0x42700000, v75
	v_exp_f32_e32 v73, v69
	v_add_f32_e32 v69, 1.0, v178
	v_exp_f32_e32 v78, v75
	v_add_f32_e32 v183, 1.0, v231
	v_rcp_f32_e32 v180, v69
	v_add_f32_e32 v69, 1.0, v237
	v_add_f32_e32 v182, 1.0, v70
	v_add_f32_e32 v184, 1.0, v235
	v_add_f32_e32 v185, 1.0, v67
	v_rcp_f32_e32 v233, v183
	v_rcp_f32_e32 v183, v69
	v_add_f32_e32 v69, 1.0, v236
	v_add_f32_e32 v68, 1.0, v65
	v_add_f32_e32 v187, 1.0, v232
	v_rcp_f32_e32 v238, v182
	v_rcp_f32_e32 v182, v184
	v_rcp_f32_e32 v184, v185
	v_rcp_f32_e32 v185, v69
	v_add_f32_e32 v69, 1.0, v72
	v_add_f32_e32 v181, 1.0, v73
	v_add_f32_e32 v186, 1.0, v64
	v_rcp_f32_e32 v76, v68
	v_rcp_f32_e32 v68, v187
	v_rcp_f32_e32 v187, v69
	v_add_f32_e32 v69, 1.0, v78
	v_rcp_f32_e32 v181, v181
	v_rcp_f32_e32 v186, v186
	v_rcp_f32_e32 v69, v69
	s_and_saveexec_b64 s[48:49], vcc
	s_cbranch_execz .LBB0_1801
	v_add_u32_e32 v75, s55, v195
	v_subrev_u32_e32 v79, 63, v75
	v_cmp_lt_i32_e32 vcc, v79, v174
	v_subrev_u32_e32 v79, 62, v75
	v_cmp_lt_i32_e64 s[0:1], v79, v174
	v_subrev_u32_e32 v79, 61, v75
	v_cmp_lt_i32_e64 s[6:7], v79, v174
	v_subrev_u32_e32 v79, 60, v75
	v_cmp_lt_i32_e64 s[8:9], v79, v174
	v_subrev_u32_e32 v79, 55, v75
	v_cmp_lt_i32_e64 s[10:11], v79, v174
	v_subrev_u32_e32 v79, 54, v75
	v_cmp_lt_i32_e64 s[12:13], v79, v174
	v_subrev_u32_e32 v79, 53, v75
	v_cmp_lt_i32_e64 s[14:15], v79, v174
	v_subrev_u32_e32 v79, 52, v75
	v_cmp_lt_i32_e64 s[16:17], v79, v174
	v_subrev_u32_e32 v79, 47, v75
	v_cmp_lt_i32_e64 s[18:19], v79, v174
	v_subrev_u32_e32 v79, 46, v75
	v_cmp_lt_i32_e64 s[20:21], v79, v174
	v_subrev_u32_e32 v79, 45, v75
	v_cmp_lt_i32_e64 s[22:23], v79, v174
	v_subrev_u32_e32 v79, 44, v75
	v_cmp_lt_i32_e64 s[24:25], v79, v174
	v_subrev_u32_e32 v79, 39, v75
	v_cmp_lt_i32_e64 s[26:27], v79, v174
	v_subrev_u32_e32 v79, 38, v75
	v_cmp_lt_i32_e64 s[28:29], v79, v174
	v_subrev_u32_e32 v79, 37, v75
	v_cmp_lt_i32_e64 s[30:31], v79, v174
	s_or_b64 s[28:29], s[30:31], s[28:29]
	s_or_b64 s[26:27], s[28:29], s[26:27]
	s_or_b64 s[24:25], s[26:27], s[24:25]
	s_or_b64 s[22:23], s[24:25], s[22:23]
	s_or_b64 s[20:21], s[22:23], s[20:21]
	s_or_b64 s[18:19], s[20:21], s[18:19]
	s_or_b64 s[16:17], s[18:19], s[16:17]
	s_or_b64 s[14:15], s[16:17], s[14:15]
	s_or_b64 s[12:13], s[14:15], s[12:13]
	s_or_b64 s[10:11], s[12:13], s[10:11]
	s_or_b64 s[8:9], s[10:11], s[8:9]
	s_or_b64 s[6:7], s[8:9], s[6:7]
	s_or_b64 s[0:1], s[6:7], s[0:1]
	s_or_b64 vcc, s[0:1], vcc
	v_subrev_u32_e32 v75, 36, v75
	v_cndmask_b32_e64 v72, 0, v72, s[30:31]
	v_cndmask_b32_e64 v236, 0, v236, s[28:29]
	v_cndmask_b32_e64 v237, 0, v237, s[26:27]
	v_cndmask_b32_e64 v232, 0, v232, s[24:25]
	v_cndmask_b32_e64 v64, 0, v64, s[22:23]
	v_cndmask_b32_e64 v67, 0, v67, s[20:21]
	v_cndmask_b32_e64 v235, 0, v235, s[18:19]
	v_cndmask_b32_e64 v231, 0, v231, s[16:17]
	v_cndmask_b32_e64 v70, 0, v70, s[14:15]
	v_cndmask_b32_e64 v73, 0, v73, s[12:13]
	v_cndmask_b32_e64 v234, 0, v234, s[10:11]
	v_cndmask_b32_e64 v175, 0, v175, s[8:9]
	v_cndmask_b32_e64 v178, 0, v178, s[6:7]
	v_cndmask_b32_e64 v65, 0, v65, s[0:1]
	v_cndmask_b32_e32 v71, 0, v71, vcc
	v_cndmask_b32_e64 v185, 1.0, v185, s[28:29]
	v_cndmask_b32_e64 v183, 1.0, v183, s[26:27]
	v_cndmask_b32_e64 v68, 1.0, v68, s[24:25]
	v_cndmask_b32_e64 v186, 1.0, v186, s[22:23]
	v_cndmask_b32_e64 v184, 1.0, v184, s[20:21]
	v_cndmask_b32_e64 v182, 1.0, v182, s[18:19]
	v_cndmask_b32_e64 v233, 1.0, v233, s[16:17]
	v_cndmask_b32_e64 v238, 1.0, v238, s[14:15]
	v_cndmask_b32_e64 v181, 1.0, v181, s[12:13]
	v_cndmask_b32_e64 v77, 1.0, v77, s[10:11]
	v_cndmask_b32_e64 v66, 1.0, v66, s[8:9]
	v_cndmask_b32_e64 v180, 1.0, v180, s[6:7]
	v_cndmask_b32_e64 v76, 1.0, v76, s[0:1]
	v_cndmask_b32_e32 v74, 1.0, v74, vcc
	v_cndmask_b32_e64 v187, 1.0, v187, s[30:31]
	v_cmp_ge_i32_e32 vcc, v75, v174
	s_and_saveexec_b64 s[0:1], vcc
	v_mov_b32_e32 v78, 0
	v_mov_b32_e32 v69, 1.0
	s_or_b64 exec, exec, s[0:1]
; #define SBAR() __builtin_amdgcn_sched_barrier(0)
; template <int D0> __device__ __forceinline__ void pv_one(f32x16& od, int vb, bf16x8 pa0, bf16x8 pa1, bf16x8 pa2, bf16x8 pa3) {
;   const s16x4 l0 = tr_read<v_rd_off(D0, 0, 0)>(vb), h0 = tr_read<v_rd_off(D0, 0, 1)>(vb), l1 = tr_read<v_rd_off(D0, 1, 0)>(vb), h1 = tr_read<v_rd_off(D0, 1, 1)>(vb);
;   const s16x4 l2 = tr_read<v_rd_off(D0, 2, 0)>(vb), h2 = tr_read<v_rd_off(D0, 2, 1)>(vb), l3 = tr_read<v_rd_off(D0, 3, 0)>(vb), h3 = tr_read<v_rd_off(D0, 3, 1)>(vb);
;   asm volatile("s_waitcnt lgkmcnt(0)" ::: "memory"); SBAR();
;     ...
;   od = __builtin_amdgcn_mfma_f32_32x32x16_bf16(pa0, PK(l0, h0), od, 0, 0, 0);
;   od = __builtin_amdgcn_mfma_f32_32x32x16_bf16(pa1, PK(l1, h1), od, 0, 0, 0);
;   od = __builtin_amdgcn_mfma_f32_32x32x16_bf16(pa2, PK(l2, h2), od, 0, 0, 0);
;   od = __builtin_amdgcn_mfma_f32_32x32x16_bf16(pa3, PK(l3, h3), od, 0, 0, 0);
; __device__ __forceinline__ void sb_half(f32x16& pz, float& run, bool need_mask, int kb, int t, int hi) {
;     ...
; #pragma unroll
;   for (int g = 0; g < 4; ++g) { l[4 * g + 2] *= l[4 * g + 3]; l[4 * g + 1] *= l[4 * g + 2]; l[4 * g] *= l[4 * g + 1]; }
;   const float cs3 = l[12], cs2 = l[8] * cs3, cs1 = l[4] * cs2, cs0 = l[0] * cs1;
;   const float off0 = cs1 * pl32_other(cs0, cs1, hi) * run;
;   const float off1 = cs2 * pl32_other(cs1, cs2, hi) * run;
;   const float off2 = cs3 * pl32_other(cs2, cs3, hi) * run;
;   const float off3 = pl32_other(cs3, 1.f, hi) * run;
;   float tot;
;   { auto rr = __builtin_amdgcn_permlane32_swap(__float_as_uint(cs0), __float_as_uint(cs0), false, false); tot = __uint_as_float(rr[0]) * __uint_as_float(rr[1]); }
; #pragma unroll
;   for (int r = 0; r < 4; ++r) {
;     pz[r] = pz[r] * l[r] * off0; pz[4 + r] = pz[4 + r] * l[4 + r] * off1;
;     pz[8 + r] = pz[8 + r] * l[8 + r] * off2; pz[12 + r] = pz[12 + r] * l[12 + r] * off3;
;   }
;   run *= tot;
; }
.LBB0_1801:
	s_or_b64 exec, exec, s[48:49]
	v_pk_mul_f32 v[186:187], v[186:187], v[68:69]
	v_add_u32_e32 v242, s56, v221
	v_pk_mul_f32 v[184:185], v[184:185], v[186:187]
	s_nop 0
	v_pk_mul_f32 v[182:183], v[182:183], v[184:185]
	v_mul_f32_e32 v184, v67, v184
	v_pk_mul_f32 v[240:241], v[182:183], v[182:183] op_sel:[0,1] op_sel_hi:[1,0]
	v_mov_b32_e32 v239, v183
	v_mov_b32_e32 v79, v240
	s_nop 1
	v_permlane32_swap_b32_e32 v79, v239
	v_mul_f32_e32 v67, v238, v233
	v_cndmask_b32_e64 v79, v79, v239, s[4:5]
	v_pk_mul_f32 v[180:181], v[180:181], v[66:67]
	v_mov_b32_e32 v75, v240
	v_mul_f32_e32 v239, v183, v79
	v_mov_b32_e32 v79, 1.0
	v_mov_b32_e32 v241, v183
	v_pk_mul_f32 v[76:77], v[76:77], v[180:181]
	s_nop 0
	v_permlane32_swap_b32_e32 v241, v79
	v_pk_mul_f32 v[74:75], v[74:75], v[76:77]
	v_cndmask_b32_e64 v241, v241, v79, s[4:5]
	v_mul_f32_e32 v79, v235, v182
	v_mul_f32_e32 v235, v237, v183
	v_pk_mul_f32 v[182:183], v[74:75], v[74:75] op_sel:[0,1] op_sel_hi:[1,0]
	v_mul_f32_e32 v185, v236, v185
	v_mov_b32_e32 v183, v182
	v_mov_b32_e32 v236, v75
	s_nop 1
	v_permlane32_swap_b32_e32 v183, v236
	v_cndmask_b32_e64 v183, v183, v236, s[4:5]
	v_mov_b32_e32 v236, v240
	v_mul_f32_e32 v183, v75, v183
	s_nop 0
	v_permlane32_swap_b32_e32 v75, v236
	v_cndmask_b32_e64 v75, v75, v236, s[4:5]
	v_mul_f32_e32 v75, v240, v75
	v_mul_f32_e32 v236, v71, v74
	v_mov_b32_e32 v71, v179
	v_mov_b32_e32 v74, v67
	v_mul_f32_e32 v73, v73, v181
	v_mov_b32_e32 v181, v183
	v_pk_mul_f32 v[70:71], v[70:71], v[74:75]
	v_mul_f32_e32 v65, v65, v76
	v_pk_mul_f32 v[74:75], v[178:179], v[180:181]
	v_mov_b32_e32 v238, v186
	v_mul_f32_e32 v178, v65, v75
	v_mov_b32_e32 v65, v179
	v_pk_mul_f32 v[64:65], v[64:65], v[238:239]
	v_mul_f32_e32 v77, v234, v77
	v_mul_f32_e32 v181, v64, v65
	v_mul_f32_e32 v64, v175, v66
	v_mul_f32_e32 v66, v64, v75
	v_mul_f32_e32 v64, v231, v233
	v_mul_f32_e32 v67, v77, v71
	v_mul_f32_e32 v76, v73, v71
	v_mul_f32_e32 v70, v70, v71
	v_mov_b32_e32 v73, v179
	v_mov_b32_e32 v240, v187
	v_mul_f32_e32 v71, v64, v71
	v_mul_f32_e32 v64, v232, v68
	v_mul_f32_e32 v77, v236, v75
	v_mul_f32_e32 v74, v74, v75
	v_pk_mul_f32 v[72:73], v[72:73], v[240:241]
	v_mul_f32_e32 v75, v64, v65
	v_mul_f32_e32 v64, v78, v69
	v_mul_f32_e32 v180, v184, v65
	v_mul_f32_e32 v183, v235, v73
	v_mul_f32_e32 v184, v185, v73
	v_mul_f32_e32 v72, v72, v73
	v_mul_f32_e32 v73, v64, v73
	v_mov_b32_e32 v64, v182
	s_nop 1
	v_permlane32_swap_b32_e32 v182, v64
	v_mul_f32_e32 v64, v182, v64
	v_mul_f32_e32 v79, v79, v65
	v_mul_f32_e32 v179, v179, v64
	v_cvt_pk_bf16_f32 v64, v77, v178
	v_cvt_pk_bf16_f32 v65, v74, v66
	v_cvt_pk_bf16_f32 v66, v67, v76
	v_cvt_pk_bf16_f32 v67, v70, v71
	v_cvt_pk_bf16_f32 v68, v79, v180
	v_cvt_pk_bf16_f32 v69, v181, v75
	v_cvt_pk_bf16_f32 v70, v183, v184
	v_cvt_pk_bf16_f32 v71, v72, v73
	ds_read_b64_tr_b16 v[72:73], v242 offset:0
	ds_read_b64_tr_b16 v[74:75], v242 offset:0x800
	ds_read_b64_tr_b16 v[76:77], v242 offset:0x1000
	ds_read_b64_tr_b16 v[78:79], v242 offset:0x1800
	ds_read_b64_tr_b16 v[180:181], v242 offset:0x2000
	ds_read_b64_tr_b16 v[182:183], v242 offset:0x2800
	ds_read_b64_tr_b16 v[184:185], v242 offset:0x3000
	ds_read_b64_tr_b16 v[186:187], v242 offset:0x3800
	s_waitcnt lgkmcnt(0)
	s_nop 0
	v_permlane32_swap_b32_e32 v64, v66
	v_permlane32_swap_b32_e32 v65, v67
	v_permlane32_swap_b32_e32 v68, v70
	v_permlane32_swap_b32_e32 v69, v71
	s_setprio 0
	v_mfma_f32_32x32x16_bf16 v[48:63], v[64:67], v[72:75], v[48:63]
	ds_read_b64_tr_b16 v[72:73], v242 offset:0x200
	ds_read_b64_tr_b16 v[74:75], v242 offset:0xa00
	s_nop 0
	v_mfma_f32_32x32x16_bf16 v[48:63], v[68:71], v[76:79], v[48:63]
	ds_read_b64_tr_b16 v[76:77], v242 offset:0x1200
	ds_read_b64_tr_b16 v[78:79], v242 offset:0x1a00
	v_mfma_f32_32x32x16_bf16 v[48:63], v[144:147], v[180:183], v[48:63]
	ds_read_b64_tr_b16 v[180:181], v242 offset:0x2200
	ds_read_b64_tr_b16 v[182:183], v242 offset:0x2a00
	ds_read_b64_tr_b16 v[232:233], v242 offset:0x3200
	ds_read_b64_tr_b16 v[234:235], v242 offset:0x3a00
	s_waitcnt lgkmcnt(0)
	v_mfma_f32_32x32x16_bf16 v[48:63], v[148:151], v[184:187], v[48:63]
	v_mfma_f32_32x32x16_bf16 v[32:47], v[64:67], v[72:75], v[32:47]
	ds_read_b64_tr_b16 v[72:73], v242 offset:0x400
	ds_read_b64_tr_b16 v[74:75], v242 offset:0xc00
	v_mfma_f32_32x32x16_bf16 v[32:47], v[68:71], v[76:79], v[32:47]
	ds_read_b64_tr_b16 v[76:77], v242 offset:0x1400
	ds_read_b64_tr_b16 v[78:79], v242 offset:0x1c00
	v_mfma_f32_32x32x16_bf16 v[32:47], v[144:147], v[180:183], v[32:47]
	ds_read_b64_tr_b16 v[180:181], v242 offset:0x2400
	ds_read_b64_tr_b16 v[182:183], v242 offset:0x2c00
	ds_read_b64_tr_b16 v[184:185], v242 offset:0x3400
	ds_read_b64_tr_b16 v[186:187], v242 offset:0x3c00
	s_waitcnt lgkmcnt(0)
	v_mfma_f32_32x32x16_bf16 v[32:47], v[148:151], v[232:235], v[32:47]
	v_mfma_f32_32x32x16_bf16 v[16:31], v[64:67], v[72:75], v[16:31]
	ds_read_b64_tr_b16 v[72:73], v242 offset:0x600
	ds_read_b64_tr_b16 v[74:75], v242 offset:0xe00
	v_mfma_f32_32x32x16_bf16 v[16:31], v[68:71], v[76:79], v[16:31]
	ds_read_b64_tr_b16 v[76:77], v242 offset:0x1600
	ds_read_b64_tr_b16 v[78:79], v242 offset:0x1e00
	v_mfma_f32_32x32x16_bf16 v[16:31], v[144:147], v[180:183], v[16:31]
	ds_read_b64_tr_b16 v[180:181], v242 offset:0x2600
	ds_read_b64_tr_b16 v[182:183], v242 offset:0x2e00
	ds_read_b64_tr_b16 v[232:233], v242 offset:0x3600
	ds_read_b64_tr_b16 v[234:235], v242 offset:0x3e00
	s_waitcnt lgkmcnt(0)
	v_mfma_f32_32x32x16_bf16 v[16:31], v[148:151], v[184:187], v[16:31]
	v_mfma_f32_32x32x16_bf16 v[0:15], v[64:67], v[72:75], v[0:15]
	v_mfma_f32_32x32x16_bf16 v[0:15], v[68:71], v[76:79], v[0:15]
	v_mfma_f32_32x32x16_bf16 v[0:15], v[144:147], v[180:183], v[0:15]
	v_mfma_f32_32x32x16_bf16 v[0:15], v[148:151], v[232:235], v[0:15]
